# ple-tile GEMM set-up and prologue LDS-DMA hoisted above the panel arrives of seams 2 and 3 (overlap with the epilogue store drain and barriers); rest as v166
# speedup vs baseline: 1.0025x; 1.0025x over previous
;     __device__ __forceinline__ bool next(int i, Unit& u) const { if (i != 0) return false; return base.next(which, u); }
;     __device__ __forceinline__ void done(const Unit& u) const {
;         if (pub == nullptr) return;
;         asm volatile("s_waitcnt vmcnt(0)" ::: "memory");
;         __builtin_amdgcn_s_barrier();
;         if (wave == 0 && lane_() == 0) { __builtin_amdgcn_fence(__ATOMIC_RELEASE, "agent"); asm volatile("s_waitcnt vmcnt(0)" ::: "memory"); __hip_atomic_fetch_add(pub + 64 * u.pm, 1u, __ATOMIC_RELAXED, __HIP_MEMORY_SCOPE_AGENT); }
;     }
; template <class Epi, class Sched, bool ALIGN_EPI = false, bool SP2 = false>
; __device__ __forceinline__ void gemm_phase(PG8_LAS unsigned char* lds, const Gemm g, const Sched& S, const Epi& E, const int wave_id) {
;     ...
;     const int wid = wave_id, tid = wave_id * 64 + lane_, lane = tid & 63, wr = wid >> 2, wc = wid & 3, fr = lane & 15, fq = lane >> 4;
;     const int K = g.K, nt = K / BK;
;     unsigned voffA[2], voffB[2];
; #pragma unroll
;     for (int i = 0; i < 2; ++i) { int R, C; stage_rc(tid * 16 + i * 8192, R, C); const int Rb = Epi::PERM ? ((R & ~31) + perm32(R & 31)) : R;
;         voffA[i] = (unsigned)(R * K + C) * 2u; voffB[i] = (unsigned)(Rb * K + C) * 2u; }
;     const size_t kstep = (size_t)(BK * 2);
;     const size_t hstep = (size_t)HALF * K * 2;
;     const size_t tstep = 2 * hstep;
;     const unsigned ldsw = (unsigned)wid * 1024u;
;     const int aoff = lds_byte(wr * 64 + fr, fq * 8), boff = lds_byte(wc * 32 + fr, fq * 8);
;     ...
;     Unit cur, nxt; int ui = 0;
;     if (!S.next(0, cur)) return;
;     f32x4 acc[2][2][4][2];
; #pragma unroll
;     for (int a = 0; a < 2; ++a)
; #pragma unroll
;         for (int b = 0; b < 2; ++b)
; #pragma unroll
;             for (int m = 0; m < 4; ++m)
; #pragma unroll
;                 for (int n = 0; n < 2; ++n) acc[a][b][m][n] = (f32x4){0.f, 0.f, 0.f, 0.f};
;     bf16x8 At[4][2], B0[2][2], B1[2][2];
;     const char* cA = (const char*)g.A + (size_t)cur.pm * tstep; const char* cB = (const char*)g.Bt + (size_t)cur.pn * tstep;
;     S.a_ready(cur);
;     if constexpr (SP2) {
;         PG8_STAGE(PG8_SB(0, 0), cB, voffB); PG8_STAGE(PG8_SB(0, 1), cB + hstep, voffB); PG8_STAGE(PG8_SA(0, 0), cA, voffA); PG8_STAGE(PG8_SA(0, 1), cA + hstep, voffA);
.LBB0_456:
	v_mbcnt_lo_u32_b32 v36, -1, 0
	v_mbcnt_hi_u32_b32 v36, -1, v36
	s_lshl_b32 s0, s66, 9
	s_waitcnt lgkmcnt(0)
	v_lshl_add_u32 v0, v36, 4, s56
	v_ashrrev_i32_e32 v1, 31, v0
	v_lshrrev_b32_e32 v1, 22, v1
	v_add_u32_e32 v1, v0, v1
	v_ashrrev_i32_e32 v1, 10, v1
	v_mul_i32_i24_e32 v2, 0x400, v1
	v_sub_u32_e32 v2, v0, v2
	v_lshrrev_b32_e32 v3, 4, v2
	v_bitop3_b32 v2, v3, v2, 32 bitop3:0x6c
	v_ashrrev_i32_e32 v4, 31, v2
	v_lshrrev_b32_e32 v4, 26, v4
	v_lshlrev_b32_e32 v3, 3, v1
	v_add_u32_e32 v4, v2, v4
	v_and_b32_e32 v3, -16, v3
	v_ashrrev_i32_e32 v5, 6, v4
	v_and_b32_e32 v4, 0xc0, v4
	v_add_u32_e32 v3, v5, v3
	v_sub_u32_e32 v2, v2, v4
	v_mov_b32_e32 v4, 1
	s_add_u32 s4, s48, s0
	v_lshlrev_b32_e32 v1, 5, v1
	v_ashrrev_i16_sdwa v2, v4, sext(v2) dst_sel:DWORD dst_unused:UNUSED_PAD src0_sel:DWORD src1_sel:BYTE_0
	v_lshlrev_b32_e32 v6, 1, v3
	v_lshrrev_b32_e32 v7, 2, v3
	v_and_b32_e32 v5, 3, v5
	s_mov_b32 s0, 0x7fffe0
	v_and_b32_e32 v1, 32, v1
	v_bfe_i32 v2, v2, 0, 16
	v_and_b32_e32 v6, 24, v6
	v_and_b32_e32 v7, 4, v7
	v_and_or_b32 v5, v3, s0, v5
	v_or3_b32 v5, v5, v7, v6
	v_add_lshl_u32 v1, v1, v2, 1
	v_add_u32_e32 v0, 0x2000, v0
	v_lshl_add_u32 v16, v3, 9, v1
	v_lshl_add_u32 v32, v5, 9, v1
	v_ashrrev_i32_e32 v1, 31, v0
	v_lshrrev_b32_e32 v1, 22, v1
	v_add_u32_e32 v1, v0, v1
	v_ashrrev_i32_e32 v1, 10, v1
	v_mul_i32_i24_e32 v2, 0x400, v1
	v_sub_u32_e32 v0, v0, v2
	v_lshrrev_b32_e32 v2, 4, v0
	v_bitop3_b32 v0, v2, v0, 32 bitop3:0x6c
	v_ashrrev_i32_e32 v3, 31, v0
	v_lshrrev_b32_e32 v3, 26, v3
	v_add_u32_e32 v3, v0, v3
	v_lshlrev_b32_e32 v2, 3, v1
	v_ashrrev_i32_e32 v5, 6, v3
	v_and_b32_e32 v3, 0xffc0, v3
	v_and_b32_e32 v2, -16, v2
	v_sub_u32_e32 v0, v0, v3
	v_add_u32_e32 v2, v5, v2
	v_lshrrev_b16_e32 v3, 7, v0
	v_and_b32_e32 v5, 3, v5
	s_addc_u32 s5, s49, 0
	v_and_b32_e32 v3, 1, v3
	v_and_or_b32 v5, v2, s0, v5
	s_lshl_b64 s[0:1], s[12:13], 17
	v_writelane_b32 v254, s4, 23
	v_add_u16_e32 v0, v0, v3
	s_add_u32 s4, s4, s0
	v_writelane_b32 v254, s5, 11
	v_lshlrev_b32_e32 v1, 5, v1
	v_ashrrev_i16_sdwa v0, v4, sext(v0) dst_sel:DWORD dst_unused:UNUSED_PAD src0_sel:DWORD src1_sel:BYTE_0
	v_lshlrev_b32_e32 v3, 1, v2
	v_lshrrev_b32_e32 v4, 2, v2
	s_addc_u32 s5, s5, s1
	s_lshl_b32 s0, s91, 17
	v_readlane_b32 s8, v254, 17
	v_and_b32_e32 v1, 32, v1
	v_bfe_i32 v0, v0, 0, 16
	v_and_b32_e32 v3, 24, v3
	v_and_b32_e32 v4, 4, v4
	v_readlane_b32 s9, v254, 18
	s_add_u32 s18, s8, s0
	s_mov_b32 m0, s59
	v_or3_b32 v3, v5, v4, v3
	v_add_lshl_u32 v0, v1, v0, 1
	s_addc_u32 s19, s9, 0
	v_lshl_add_u32 v34, v3, 9, v0
	global_load_lds_dwordx4 v32, s[18:19]
	s_mov_b32 m0, s60
	s_add_u32 s20, s18, 0x10000
	global_load_lds_dwordx4 v34, s[18:19]
	s_addc_u32 s21, s19, 0
	s_mov_b32 m0, s61
	v_lshl_add_u32 v18, v2, 9, v0
	global_load_lds_dwordx4 v32, s[20:21]
	s_mov_b32 m0, s62
	s_add_u32 s0, s4, 0x10000
	global_load_lds_dwordx4 v34, s[20:21]
	s_mov_b32 m0, s33
	s_addc_u32 s1, s5, 0
	global_load_lds_dwordx4 v16, s[4:5]
	s_mov_b32 m0, s63
	v_mov_b32_e32 v33, 0
	global_load_lds_dwordx4 v18, s[4:5]
	s_mov_b32 m0, s69
	v_mov_b32_e32 v35, v33
	global_load_lds_dwordx4 v16, s[0:1]
	s_mov_b32 m0, s70
	v_mov_b32_e32 v17, v33
	global_load_lds_dwordx4 v18, s[0:1]
	v_mov_b32_e32 v19, v33
	v_cndmask_b32_e64 v0, 0, 1, s[2:3]
	v_lshl_add_u64 v[28:29], s[18:19], 0, v[32:33]
	v_lshl_add_u64 v[30:31], s[18:19], 0, v[34:35]
	v_lshl_add_u64 v[26:27], s[20:21], 0, v[32:33]
	v_lshl_add_u64 v[20:21], s[20:21], 0, v[34:35]
	v_lshl_add_u64 v[22:23], s[4:5], 0, v[16:17]
	v_lshl_add_u64 v[24:25], s[4:5], 0, v[18:19]
	v_lshl_add_u64 v[12:13], s[0:1], 0, v[16:17]
	v_cmp_ne_u32_e64 s[8:9], 1, v0
	v_lshl_add_u64 v[14:15], s[0:1], 0, v[18:19]
	s_waitcnt vmcnt(0)
	s_barrier
	s_waitcnt vmcnt(0)
	s_and_b64 vcc, exec, s[94:95]
	s_barrier
	s_cbranch_vccnz .LBB0_482
	v_mbcnt_lo_u32_b32 v0, -1, 0
	v_mbcnt_hi_u32_b32 v0, -1, v0
	s_nop 0
	v_cmp_eq_u32_e32 vcc, 0, v0
	s_and_saveexec_b64 s[100:101], vcc
	s_cbranch_execz .LBB0_481
	s_cmp_eq_u32 s98, 0
	s_cbranch_scc1 .Lpa2_fast
	buffer_wbl2 sc1
	s_waitcnt vmcnt(0)

; #define PG8_STAGE(bufoff, gbase, voff) do { _Pragma("unroll") for (int _i = 0; _i < 2; ++_i) \
;         __builtin_amdgcn_global_load_lds((const unsigned*)((const char*)(gbase) + (voff)[_i]), (PG8_LAS unsigned*)(lds + (bufoff) + ldsw + _i * 8192), 16, 0, 0); } while (0)
; #define PG8_LDA(dst, b, h) do { _Pragma("unroll") for (int m = 0; m < 4; ++m) _Pragma("unroll") for (int k = 0; k < 2; ++k) dst[m][k] = *(const PG8_LAS bf16x8*)(lds + PG8_SA(b, h) + aoff + m * 2048 + k * 1024); } while (0)
; #define PG8_LDB(dst, b, h) do { _Pragma("unroll") for (int n = 0; n < 2; ++n) _Pragma("unroll") for (int k = 0; k < 2; ++k) dst[n][k] = *(const PG8_LAS bf16x8*)(lds + PG8_SB(b, h) + boff + n * 2048 + k * 1024); } while (0)
; #define PG8_MMA(ai, bj, At, Bt) do { __builtin_amdgcn_s_setprio(1); _Pragma("unroll") for (int m = 0; m < 4; ++m) _Pragma("unroll") for (int n = 0; n < 2; ++n) _Pragma("unroll") for (int k = 0; k < 2; ++k) \
;         acc[ai][bj][m][n] = __builtin_amdgcn_mfma_f32_16x16x32_bf16(Bt[n][k], At[m][k], acc[ai][bj][m][n], 0, 0, 0); __builtin_amdgcn_s_setprio(0); } while (0)
; #define PG8_WAIT_V(n) asm volatile("s_waitcnt vmcnt(" #n ")" ::: "memory")
; #define PG8_WAIT_L(n) asm volatile("s_waitcnt lgkmcnt(" #n ")" ::: "memory")
; #define PG8_BAR __builtin_amdgcn_s_barrier()
; #define PG8_SCHED __builtin_amdgcn_sched_barrier(0)
; template <class Epi, class Sched, bool ALIGN_EPI = false, bool SP2 = false>
; __device__ __forceinline__ void gemm_phase(PG8_LAS unsigned char* lds, const Gemm g, const Sched& S, const Epi& E, const int wave_id) {
;     ...
;         PG8_STAGE(PG8_SB(0, 0), cB, voffB); PG8_STAGE(PG8_SB(0, 1), cB + hstep, voffB); PG8_STAGE(PG8_SA(0, 0), cA, voffA); PG8_STAGE(PG8_SA(0, 1), cA + hstep, voffA);
;         if (wr == 1) PG8_BAR;
;         PG8_WAIT_V(2); PG8_BAR;
;         PG8_STAGE(PG8_SB(1, 0), cB + kstep, voffB); PG8_STAGE(PG8_SA(1, 0), cA + kstep, voffA); PG8_STAGE(PG8_SB(1, 1), cB + hstep + kstep, voffB);
;         PG8_WAIT_V(6); PG8_BAR;
;     ...
;             PG8_LDB(B0, 0, 0); PG8_LDB(B1, 0, 1); PG8_SCHED; PG8_LDA(At, 0, 0); PG8_STAGE(PG8_SA(1, 1), a1 + hstep, voffA);
;             PG8_WAIT_V(8); PG8_WAIT_L(0); PG8_BAR; PG8_MMA(0, 0, At, B0); PG8_MMA(0, 1, At, B1); PG8_BAR; PG8_SCHED;
;             PG8_LDA(At, 0, 1); PG8_STAGE(PG8_SB(0, 0), b2, voffB); PG8_STAGE(PG8_SB(0, 1), b2 + hstep, voffB); PG8_STAGE(PG8_SA(0, 0), a2, voffA);
.LBB0_481:
	s_or_b64 exec, exec, s[100:101]
.LBB0_482:
	s_andn2_b64 vcc, exec, s[2:3]
	s_cbranch_vccnz .LBB0_484
	s_barrier
.LBB0_484:
	s_mov_b64 s[0:1], 0x80
	s_mov_b32 m0, s87
	v_lshl_add_u64 v[4:5], v[28:29], 0, s[0:1]
	s_waitcnt vmcnt(2)
	s_barrier
	global_load_lds_dwordx4 v[4:5], off
	v_lshl_add_u64 v[6:7], v[30:31], 0, s[0:1]
	s_mov_b32 m0, s88
	v_lshl_add_u64 v[0:1], v[22:23], 0, s[0:1]
	global_load_lds_dwordx4 v[6:7], off
	s_mov_b32 m0, s73
	s_add_u32 s22, s18, 0x10080
	global_load_lds_dwordx4 v[0:1], off
	v_lshl_add_u64 v[2:3], v[24:25], 0, s[0:1]
	s_mov_b32 m0, s74
	s_addc_u32 s23, s19, 0
	global_load_lds_dwordx4 v[2:3], off
	v_lshl_add_u64 v[8:9], s[22:23], 0, v[32:33]
	s_mov_b32 m0, s89
	v_lshl_add_u64 v[10:11], s[22:23], 0, v[34:35]
	global_load_lds_dwordx4 v[8:9], off
	s_mov_b32 m0, s90
	v_lshrrev_b32_e32 v38, 1, v36
	global_load_lds_dwordx4 v[10:11], off
	v_and_b32_e32 v128, 24, v38
	v_and_b32_e32 v37, 15, v36
	v_lshlrev_b32_e32 v39, 1, v128
	v_lshlrev_b32_e32 v36, 2, v36
	v_or_b32_e32 v129, s57, v37
	v_lshl_or_b32 v37, v37, 6, v39
	v_and_b32_e32 v36, 32, v36
	v_lshlrev_b32_e32 v38, 6, v129
	s_movk_i32 s0, 0x3c0
	v_bitop3_b32 v70, v37, s93, v36 bitop3:0xde
	v_and_or_b32 v68, v38, s0, v39
	v_lshlrev_b32_e32 v38, 2, v129
	v_add_u32_e32 v233, s78, v70
	v_and_b32_e32 v69, 32, v38
	s_waitcnt vmcnt(6)
	s_barrier
	v_add_u32_e32 v232, s77, v70
	ds_read_b128 v[36:39], v233 offset:3072
	ds_read_b128 v[40:43], v233 offset:2048
	ds_read_b128 v[44:47], v233 offset:1024
	ds_read_b128 v[48:51], v233
	ds_read_b128 v[52:55], v232 offset:3072
	ds_read_b128 v[56:59], v232 offset:2048
	ds_read_b128 v[60:63], v232 offset:1024
	ds_read_b128 v[64:67], v232
	v_bitop3_b32 v68, v68, s64, v69 bitop3:0xde
	v_writelane_b32 v254, s93, 9
	v_add_u32_e32 v242, 0, v68
	v_add_u32_e32 v234, s85, v70
	v_add_u32_e32 v235, s86, v70
	s_add_u32 s0, s4, 0x10080
	s_addc_u32 s1, s5, 0
	s_mov_b32 m0, s79
	v_lshl_add_u64 v[100:101], s[0:1], 0, v[16:17]
	ds_read_b128 v[68:71], v242
	ds_read_b128 v[72:75], v242 offset:1024
	ds_read_b128 v[76:79], v242 offset:2048
	ds_read_b128 v[80:83], v242 offset:3072
	ds_read_b128 v[84:87], v242 offset:4096
	ds_read_b128 v[88:91], v242 offset:5120
	ds_read_b128 v[92:95], v242 offset:6144
	ds_read_b128 v[96:99], v242 offset:7168
	global_load_lds_dwordx4 v[100:101], off
	v_lshl_add_u64 v[100:101], s[0:1], 0, v[18:19]
	s_mov_b32 m0, s80
	s_nop 0
	global_load_lds_dwordx4 v[100:101], off
	s_waitcnt vmcnt(8)
	s_waitcnt lgkmcnt(0)
	s_barrier
	s_waitcnt lgkmcnt(0)
	v_mfma_f32_16x16x32_bf16 v[100:103], v[64:67], v[68:71], 0
	v_mfma_f32_16x16x32_bf16 v[104:107], v[56:59], v[68:71], 0
	v_mfma_f32_16x16x32_bf16 v[108:111], v[64:67], v[76:79], 0
	v_mfma_f32_16x16x32_bf16 v[112:115], v[56:59], v[76:79], 0
	v_mfma_f32_16x16x32_bf16 v[116:119], v[64:67], v[84:87], 0
	v_mfma_f32_16x16x32_bf16 v[120:123], v[56:59], v[84:87], 0
	v_mfma_f32_16x16x32_bf16 v[124:127], v[64:67], v[92:95], 0
	v_mfma_f32_16x16x32_bf16 v[100:103], v[60:63], v[72:75], v[100:103]
	v_mfma_f32_16x16x32_bf16 v[104:107], v[52:55], v[72:75], v[104:107]
	v_mfma_f32_16x16x32_bf16 v[108:111], v[60:63], v[80:83], v[108:111]
	v_mfma_f32_16x16x32_bf16 v[112:115], v[52:55], v[80:83], v[112:115]
	v_mfma_f32_16x16x32_bf16 v[116:119], v[60:63], v[88:91], v[116:119]
	v_mfma_f32_16x16x32_bf16 v[120:123], v[52:55], v[88:91], v[120:123]
	v_mfma_f32_16x16x32_bf16 v[124:127], v[60:63], v[96:99], v[124:127]
	v_mfma_f32_16x16x32_bf16 v[130:133], v[56:59], v[92:95], 0
	v_mfma_f32_16x16x32_bf16 v[130:133], v[52:55], v[96:99], v[130:133]
	v_mfma_f32_16x16x32_bf16 v[134:137], v[48:51], v[68:71], 0
	v_mfma_f32_16x16x32_bf16 v[68:71], v[40:43], v[68:71], 0
	v_mfma_f32_16x16x32_bf16 v[134:137], v[44:47], v[72:75], v[134:137]
	v_mfma_f32_16x16x32_bf16 v[68:71], v[36:39], v[72:75], v[68:71]
	v_mfma_f32_16x16x32_bf16 v[72:75], v[48:51], v[76:79], 0
	v_mfma_f32_16x16x32_bf16 v[76:79], v[40:43], v[76:79], 0
	v_mfma_f32_16x16x32_bf16 v[72:75], v[44:47], v[80:83], v[72:75]
	v_mfma_f32_16x16x32_bf16 v[76:79], v[36:39], v[80:83], v[76:79]
	v_mfma_f32_16x16x32_bf16 v[80:83], v[48:51], v[84:87], 0
	v_mfma_f32_16x16x32_bf16 v[84:87], v[40:43], v[84:87], 0
	v_mfma_f32_16x16x32_bf16 v[80:83], v[44:47], v[88:91], v[80:83]
	v_mfma_f32_16x16x32_bf16 v[84:87], v[36:39], v[88:91], v[84:87]
	v_mfma_f32_16x16x32_bf16 v[88:91], v[48:51], v[92:95], 0
	v_mfma_f32_16x16x32_bf16 v[92:95], v[40:43], v[92:95], 0
	v_mfma_f32_16x16x32_bf16 v[88:91], v[44:47], v[96:99], v[88:91]
	v_mfma_f32_16x16x32_bf16 v[92:95], v[36:39], v[96:99], v[92:95]
	s_barrier
	s_mov_b64 s[0:1], 0x100
	s_mov_b32 m0, s81
	v_lshl_add_u64 v[166:167], v[28:29], 0, s[0:1]
	s_add_u32 s24, s18, 0x10100
	ds_read_b128 v[96:99], v242 offset:16384
	ds_read_b128 v[138:141], v242 offset:17408
	ds_read_b128 v[142:145], v242 offset:18432
	ds_read_b128 v[146:149], v242 offset:19456
	ds_read_b128 v[150:153], v242 offset:20480
	ds_read_b128 v[154:157], v242 offset:21504
	ds_read_b128 v[158:161], v242 offset:22528
	ds_read_b128 v[162:165], v242 offset:23552
	global_load_lds_dwordx4 v[166:167], off
	v_lshl_add_u64 v[166:167], v[30:31], 0, s[0:1]
	s_mov_b32 m0, s82
	s_addc_u32 s25, s19, 0
	global_load_lds_dwordx4 v[166:167], off
	v_lshl_add_u64 v[166:167], s[24:25], 0, v[32:33]
	s_mov_b32 m0, s83
	s_nop 0
	global_load_lds_dwordx4 v[166:167], off
	v_lshl_add_u64 v[166:167], s[24:25], 0, v[34:35]
	s_mov_b32 m0, s84
	s_nop 0
	global_load_lds_dwordx4 v[166:167], off
	v_lshl_add_u64 v[166:167], v[22:23], 0, s[0:1]
	s_mov_b32 m0, s33
	s_nop 0
	global_load_lds_dwordx4 v[166:167], off
	v_lshl_add_u64 v[166:167], v[24:25], 0, s[0:1]
	s_mov_b32 m0, s63
	s_nop 0
	global_load_lds_dwordx4 v[166:167], off
	s_waitcnt vmcnt(8)
	s_waitcnt lgkmcnt(0)
	s_barrier
; #define PG8_STAGE(bufoff, gbase, voff) do { _Pragma("unroll") for (int _i = 0; _i < 2; ++_i) \
;         __builtin_amdgcn_global_load_lds((const unsigned*)((const char*)(gbase) + (voff)[_i]), (PG8_LAS unsigned*)(lds + (bufoff) + ldsw + _i * 8192), 16, 0, 0); } while (0)
; #define PG8_LDA(dst, b, h) do { _Pragma("unroll") for (int m = 0; m < 4; ++m) _Pragma("unroll") for (int k = 0; k < 2; ++k) dst[m][k] = *(const PG8_LAS bf16x8*)(lds + PG8_SA(b, h) + aoff + m * 2048 + k * 1024); } while (0)
; #define PG8_LDB(dst, b, h) do { _Pragma("unroll") for (int n = 0; n < 2; ++n) _Pragma("unroll") for (int k = 0; k < 2; ++k) dst[n][k] = *(const PG8_LAS bf16x8*)(lds + PG8_SB(b, h) + boff + n * 2048 + k * 1024); } while (0)
; #define PG8_MMA(ai, bj, At, Bt) do { __builtin_amdgcn_s_setprio(1); _Pragma("unroll") for (int m = 0; m < 4; ++m) _Pragma("unroll") for (int n = 0; n < 2; ++n) _Pragma("unroll") for (int k = 0; k < 2; ++k) \
;         acc[ai][bj][m][n] = __builtin_amdgcn_mfma_f32_16x16x32_bf16(Bt[n][k], At[m][k], acc[ai][bj][m][n], 0, 0, 0); __builtin_amdgcn_s_setprio(0); } while (0)
; #define PG8_WAIT_V(n) asm volatile("s_waitcnt vmcnt(" #n ")" ::: "memory")
; #define PG8_WAIT_L(n) asm volatile("s_waitcnt lgkmcnt(" #n ")" ::: "memory")
; #define PG8_BAR __builtin_amdgcn_s_barrier()
; #define PG8_SCHED __builtin_amdgcn_sched_barrier(0)
; template <class Epi, class Sched, bool ALIGN_EPI = false, bool SP2 = false>
; __device__ __forceinline__ void gemm_phase(PG8_LAS unsigned char* lds, const Gemm g, const Sched& S, const Epi& E, const int wave_id) {
;     ...
;             PG8_WAIT_V(8); PG8_WAIT_L(0); PG8_BAR; PG8_MMA(1, 0, At, B0); PG8_MMA(1, 1, At, B1); PG8_BAR; PG8_SCHED;
;             PG8_LDB(B0, 1, 0); PG8_LDB(B1, 1, 1); PG8_SCHED; PG8_LDA(At, 1, 0); PG8_STAGE(PG8_SA(0, 1), a2 + hstep, voffA);
;             PG8_WAIT_V(8); PG8_WAIT_L(0); PG8_BAR; PG8_MMA(0, 0, At, B0); PG8_MMA(0, 1, At, B1); PG8_BAR; PG8_SCHED;
	s_waitcnt lgkmcnt(0)
	v_mfma_f32_16x16x32_bf16 v[166:169], v[64:67], v[96:99], 0
	v_mfma_f32_16x16x32_bf16 v[170:173], v[56:59], v[96:99], 0
	v_mfma_f32_16x16x32_bf16 v[174:177], v[64:67], v[142:145], 0
	v_mfma_f32_16x16x32_bf16 v[178:181], v[56:59], v[142:145], 0
	v_mfma_f32_16x16x32_bf16 v[182:185], v[64:67], v[150:153], 0
	v_mfma_f32_16x16x32_bf16 v[186:189], v[56:59], v[150:153], 0
	v_mfma_f32_16x16x32_bf16 v[64:67], v[64:67], v[158:161], 0
	v_mfma_f32_16x16x32_bf16 v[56:59], v[56:59], v[158:161], 0
	v_mfma_f32_16x16x32_bf16 v[166:169], v[60:63], v[138:141], v[166:169]
	v_mfma_f32_16x16x32_bf16 v[170:173], v[52:55], v[138:141], v[170:173]
	v_mfma_f32_16x16x32_bf16 v[174:177], v[60:63], v[146:149], v[174:177]
	v_mfma_f32_16x16x32_bf16 v[178:181], v[52:55], v[146:149], v[178:181]
	v_mfma_f32_16x16x32_bf16 v[182:185], v[60:63], v[154:157], v[182:185]
	v_mfma_f32_16x16x32_bf16 v[186:189], v[52:55], v[154:157], v[186:189]
	v_mfma_f32_16x16x32_bf16 v[60:63], v[60:63], v[162:165], v[64:67]
	v_mfma_f32_16x16x32_bf16 v[52:55], v[52:55], v[162:165], v[56:59]
	v_mfma_f32_16x16x32_bf16 v[56:59], v[48:51], v[96:99], 0
	v_mfma_f32_16x16x32_bf16 v[64:67], v[40:43], v[96:99], 0
	v_mfma_f32_16x16x32_bf16 v[56:59], v[44:47], v[138:141], v[56:59]
	v_mfma_f32_16x16x32_bf16 v[64:67], v[36:39], v[138:141], v[64:67]
	v_mfma_f32_16x16x32_bf16 v[96:99], v[48:51], v[142:145], 0
	v_mfma_f32_16x16x32_bf16 v[138:141], v[40:43], v[142:145], 0
	v_mfma_f32_16x16x32_bf16 v[96:99], v[44:47], v[146:149], v[96:99]
	v_mfma_f32_16x16x32_bf16 v[138:141], v[36:39], v[146:149], v[138:141]
	v_mfma_f32_16x16x32_bf16 v[142:145], v[48:51], v[150:153], 0
	v_mfma_f32_16x16x32_bf16 v[146:149], v[40:43], v[150:153], 0
	v_mfma_f32_16x16x32_bf16 v[48:51], v[48:51], v[158:161], 0
	v_mfma_f32_16x16x32_bf16 v[40:43], v[40:43], v[158:161], 0
	v_mfma_f32_16x16x32_bf16 v[142:145], v[44:47], v[154:157], v[142:145]
	v_mfma_f32_16x16x32_bf16 v[146:149], v[36:39], v[154:157], v[146:149]
	v_mfma_f32_16x16x32_bf16 v[44:47], v[44:47], v[162:165], v[48:51]
	v_mfma_f32_16x16x32_bf16 v[36:39], v[36:39], v[162:165], v[40:43]
	s_barrier
	s_nop 1
	ds_read_b128 v[40:43], v234
	ds_read_b128 v[48:51], v234 offset:1024
	ds_read_b128 v[150:153], v234 offset:2048
	ds_read_b128 v[154:157], v234 offset:3072
	ds_read_b128 v[158:161], v235
	ds_read_b128 v[162:165], v235 offset:1024
	ds_read_b128 v[190:193], v235 offset:2048
	ds_read_b128 v[194:197], v235 offset:3072
	s_add_u32 s0, s4, 0x10100
	s_addc_u32 s1, s5, 0
	s_mov_b32 m0, s69
	v_lshl_add_u64 v[230:231], s[0:1], 0, v[16:17]
	ds_read_b128 v[198:201], v242 offset:32768
	ds_read_b128 v[202:205], v242 offset:33792
	ds_read_b128 v[206:209], v242 offset:34816
	ds_read_b128 v[210:213], v242 offset:35840
	ds_read_b128 v[214:217], v242 offset:36864
	ds_read_b128 v[218:221], v242 offset:37888
	ds_read_b128 v[222:225], v242 offset:38912
	ds_read_b128 v[226:229], v242 offset:39936
	global_load_lds_dwordx4 v[230:231], off
	v_lshl_add_u64 v[230:231], s[0:1], 0, v[18:19]
	s_mov_b32 m0, s70
	s_nop 0
	global_load_lds_dwordx4 v[230:231], off
	s_waitcnt vmcnt(8)
	s_waitcnt lgkmcnt(0)
	s_barrier
	s_waitcnt lgkmcnt(0)
	v_mfma_f32_16x16x32_bf16 v[100:103], v[40:43], v[198:201], v[100:103]
	v_mfma_f32_16x16x32_bf16 v[104:107], v[150:153], v[198:201], v[104:107]
	v_mfma_f32_16x16x32_bf16 v[108:111], v[40:43], v[206:209], v[108:111]
	v_mfma_f32_16x16x32_bf16 v[112:115], v[150:153], v[206:209], v[112:115]
	v_mfma_f32_16x16x32_bf16 v[116:119], v[40:43], v[214:217], v[116:119]
	v_mfma_f32_16x16x32_bf16 v[120:123], v[150:153], v[214:217], v[120:123]
	v_mfma_f32_16x16x32_bf16 v[124:127], v[40:43], v[222:225], v[124:127]
	v_mfma_f32_16x16x32_bf16 v[100:103], v[48:51], v[202:205], v[100:103]
	v_mfma_f32_16x16x32_bf16 v[104:107], v[154:157], v[202:205], v[104:107]
	v_mfma_f32_16x16x32_bf16 v[108:111], v[48:51], v[210:213], v[108:111]
	v_mfma_f32_16x16x32_bf16 v[112:115], v[154:157], v[210:213], v[112:115]
	v_mfma_f32_16x16x32_bf16 v[116:119], v[48:51], v[218:221], v[116:119]
	v_mfma_f32_16x16x32_bf16 v[120:123], v[154:157], v[218:221], v[120:123]
	v_mfma_f32_16x16x32_bf16 v[124:127], v[48:51], v[226:229], v[124:127]
	v_mfma_f32_16x16x32_bf16 v[130:133], v[150:153], v[222:225], v[130:133]
	v_mfma_f32_16x16x32_bf16 v[130:133], v[154:157], v[226:229], v[130:133]
	v_mfma_f32_16x16x32_bf16 v[68:71], v[190:193], v[198:201], v[68:71]
	v_mfma_f32_16x16x32_bf16 v[72:75], v[158:161], v[206:209], v[72:75]
	v_mfma_f32_16x16x32_bf16 v[76:79], v[190:193], v[206:209], v[76:79]
	v_mfma_f32_16x16x32_bf16 v[80:83], v[158:161], v[214:217], v[80:83]
	v_mfma_f32_16x16x32_bf16 v[84:87], v[190:193], v[214:217], v[84:87]
	v_mfma_f32_16x16x32_bf16 v[88:91], v[158:161], v[222:225], v[88:91]
	v_mfma_f32_16x16x32_bf16 v[92:95], v[190:193], v[222:225], v[92:95]
	v_mfma_f32_16x16x32_bf16 v[134:137], v[158:161], v[198:201], v[134:137]
	v_mfma_f32_16x16x32_bf16 v[68:71], v[194:197], v[202:205], v[68:71]
	v_mfma_f32_16x16x32_bf16 v[72:75], v[162:165], v[210:213], v[72:75]
	v_mfma_f32_16x16x32_bf16 v[76:79], v[194:197], v[210:213], v[76:79]
	v_mfma_f32_16x16x32_bf16 v[80:83], v[162:165], v[218:221], v[80:83]
	v_mfma_f32_16x16x32_bf16 v[84:87], v[194:197], v[218:221], v[84:87]
	v_mfma_f32_16x16x32_bf16 v[88:91], v[162:165], v[226:229], v[88:91]
	v_mfma_f32_16x16x32_bf16 v[92:95], v[194:197], v[226:229], v[92:95]
	v_mfma_f32_16x16x32_bf16 v[134:137], v[162:165], v[202:205], v[134:137]
	s_barrier
; #define PG8_STAGE(bufoff, gbase, voff) do { _Pragma("unroll") for (int _i = 0; _i < 2; ++_i) \
;         __builtin_amdgcn_global_load_lds((const unsigned*)((const char*)(gbase) + (voff)[_i]), (PG8_LAS unsigned*)(lds + (bufoff) + ldsw + _i * 8192), 16, 0, 0); } while (0)
; #define PG8_LDA(dst, b, h) do { _Pragma("unroll") for (int m = 0; m < 4; ++m) _Pragma("unroll") for (int k = 0; k < 2; ++k) dst[m][k] = *(const PG8_LAS bf16x8*)(lds + PG8_SA(b, h) + aoff + m * 2048 + k * 1024); } while (0)
; #define PG8_MMA(ai, bj, At, Bt) do { __builtin_amdgcn_s_setprio(1); _Pragma("unroll") for (int m = 0; m < 4; ++m) _Pragma("unroll") for (int n = 0; n < 2; ++n) _Pragma("unroll") for (int k = 0; k < 2; ++k) \
;         acc[ai][bj][m][n] = __builtin_amdgcn_mfma_f32_16x16x32_bf16(Bt[n][k], At[m][k], acc[ai][bj][m][n], 0, 0, 0); __builtin_amdgcn_s_setprio(0); } while (0)
; #define PG8_WAIT_V(n) asm volatile("s_waitcnt vmcnt(" #n ")" ::: "memory")
; #define PG8_WAIT_L(n) asm volatile("s_waitcnt lgkmcnt(" #n ")" ::: "memory")
; #define PG8_BAR __builtin_amdgcn_s_barrier()
; #define PG8_SCHED __builtin_amdgcn_sched_barrier(0)
; template <class Epi, class Sched, bool ALIGN_EPI = false, bool SP2 = false>
; __device__ __forceinline__ void gemm_phase(PG8_LAS unsigned char* lds, const Gemm g, const Sched& S, const Epi& E, const int wave_id) {
;     ...
;             PG8_WAIT_V(8); PG8_WAIT_L(0); PG8_BAR; PG8_MMA(0, 0, At, B0); PG8_MMA(0, 1, At, B1); PG8_BAR; PG8_SCHED;
;             PG8_LDA(At, 1, 1); PG8_STAGE(PG8_SB(1, 0), b3, voffB); PG8_STAGE(PG8_SB(1, 1), b3 + hstep, voffB); PG8_STAGE(PG8_SA(1, 0), a3, voffA);
;             PG8_WAIT_V(8); PG8_WAIT_L(0); PG8_BAR; PG8_MMA(1, 0, At, B0); PG8_MMA(1, 1, At, B1); PG8_BAR; PG8_SCHED;
;             } else {
	s_mov_b64 s[0:1], 0x180
	s_mov_b32 m0, s87
	v_lshl_add_u64 v[230:231], v[28:29], 0, s[0:1]
	s_add_u32 s26, s18, 0x10180
	ds_read_b128 v[198:201], v242 offset:49152
	ds_read_b128 v[202:205], v242 offset:50176
	ds_read_b128 v[206:209], v242 offset:51200
	ds_read_b128 v[210:213], v242 offset:52224
	ds_read_b128 v[214:217], v242 offset:53248
	ds_read_b128 v[218:221], v242 offset:54272
	ds_read_b128 v[222:225], v242 offset:55296
	ds_read_b128 v[226:229], v242 offset:56320
	global_load_lds_dwordx4 v[230:231], off
	v_lshl_add_u64 v[230:231], v[30:31], 0, s[0:1]
	s_mov_b32 m0, s88
	s_addc_u32 s27, s19, 0
	global_load_lds_dwordx4 v[230:231], off
	v_lshl_add_u64 v[32:33], s[26:27], 0, v[32:33]
	s_mov_b32 m0, s89
	s_nop 0
	global_load_lds_dwordx4 v[32:33], off
	v_lshl_add_u64 v[32:33], s[26:27], 0, v[34:35]
	s_mov_b32 m0, s90
	s_nop 0
	global_load_lds_dwordx4 v[32:33], off
	v_lshl_add_u64 v[32:33], v[22:23], 0, s[0:1]
	s_mov_b32 m0, s73
	s_nop 0
	global_load_lds_dwordx4 v[32:33], off
	v_lshl_add_u64 v[32:33], v[24:25], 0, s[0:1]
	s_mov_b32 m0, s74
	s_nop 0
	global_load_lds_dwordx4 v[32:33], off
	s_waitcnt vmcnt(8)
	s_waitcnt lgkmcnt(0)
	s_barrier
	s_waitcnt lgkmcnt(0)
	v_mfma_f32_16x16x32_bf16 v[32:35], v[40:43], v[198:201], v[166:169]
	v_mfma_f32_16x16x32_bf16 v[166:169], v[150:153], v[198:201], v[170:173]
	v_mfma_f32_16x16x32_bf16 v[170:173], v[40:43], v[206:209], v[174:177]
	v_mfma_f32_16x16x32_bf16 v[174:177], v[150:153], v[206:209], v[178:181]
	v_mfma_f32_16x16x32_bf16 v[178:181], v[40:43], v[214:217], v[182:185]
	v_mfma_f32_16x16x32_bf16 v[40:43], v[40:43], v[222:225], v[60:63]
	v_mfma_f32_16x16x32_bf16 v[32:35], v[48:51], v[202:205], v[32:35]
	v_mfma_f32_16x16x32_bf16 v[170:173], v[48:51], v[210:213], v[170:173]
	v_mfma_f32_16x16x32_bf16 v[178:181], v[48:51], v[218:221], v[178:181]
	v_mfma_f32_16x16x32_bf16 v[40:43], v[48:51], v[226:229], v[40:43]
	v_mfma_f32_16x16x32_bf16 v[48:51], v[150:153], v[222:225], v[52:55]
	v_mfma_f32_16x16x32_bf16 v[182:185], v[150:153], v[214:217], v[186:189]
	v_mfma_f32_16x16x32_bf16 v[48:51], v[154:157], v[226:229], v[48:51]
	v_mfma_f32_16x16x32_bf16 v[166:169], v[154:157], v[202:205], v[166:169]
	v_mfma_f32_16x16x32_bf16 v[174:177], v[154:157], v[210:213], v[174:177]
	v_mfma_f32_16x16x32_bf16 v[182:185], v[154:157], v[218:221], v[182:185]
	v_mfma_f32_16x16x32_bf16 v[52:55], v[158:161], v[198:201], v[56:59]
	v_mfma_f32_16x16x32_bf16 v[56:59], v[190:193], v[198:201], v[64:67]
	v_mfma_f32_16x16x32_bf16 v[60:63], v[158:161], v[206:209], v[96:99]
	v_mfma_f32_16x16x32_bf16 v[64:67], v[190:193], v[206:209], v[138:141]
	v_mfma_f32_16x16x32_bf16 v[96:99], v[158:161], v[214:217], v[142:145]
	v_mfma_f32_16x16x32_bf16 v[44:47], v[158:161], v[222:225], v[44:47]
	v_mfma_f32_16x16x32_bf16 v[36:39], v[190:193], v[222:225], v[36:39]
	v_mfma_f32_16x16x32_bf16 v[52:55], v[162:165], v[202:205], v[52:55]
	v_mfma_f32_16x16x32_bf16 v[56:59], v[194:197], v[202:205], v[56:59]
	v_mfma_f32_16x16x32_bf16 v[60:63], v[162:165], v[210:213], v[60:63]
	v_mfma_f32_16x16x32_bf16 v[64:67], v[194:197], v[210:213], v[64:67]
	v_mfma_f32_16x16x32_bf16 v[96:99], v[162:165], v[218:221], v[96:99]
	v_mfma_f32_16x16x32_bf16 v[138:141], v[190:193], v[214:217], v[146:149]
	v_mfma_f32_16x16x32_bf16 v[44:47], v[162:165], v[226:229], v[44:47]
	v_mfma_f32_16x16x32_bf16 v[36:39], v[194:197], v[226:229], v[36:39]
	v_mfma_f32_16x16x32_bf16 v[138:141], v[194:197], v[218:221], v[138:141]
	s_barrier
	ds_read_b128 v[142:145], v232
	ds_read_b128 v[146:149], v232 offset:1024
	ds_read_b128 v[150:153], v232 offset:2048
	ds_read_b128 v[154:157], v232 offset:3072
	ds_read_b128 v[158:161], v233
	ds_read_b128 v[162:165], v233 offset:1024
	ds_read_b128 v[186:189], v233 offset:2048
	ds_read_b128 v[190:193], v233 offset:3072
	s_add_u32 s0, s4, 0x10180
	s_addc_u32 s1, s5, 0
	s_mov_b32 m0, s79
	v_lshl_add_u64 v[16:17], s[0:1], 0, v[16:17]
	ds_read_b128 v[194:197], v242
	ds_read_b128 v[198:201], v242 offset:1024
	ds_read_b128 v[202:205], v242 offset:2048
	ds_read_b128 v[206:209], v242 offset:3072
	ds_read_b128 v[210:213], v242 offset:4096
	ds_read_b128 v[214:217], v242 offset:5120
	ds_read_b128 v[218:221], v242 offset:6144
	ds_read_b128 v[222:225], v242 offset:7168
	global_load_lds_dwordx4 v[16:17], off
	v_lshl_add_u64 v[16:17], s[0:1], 0, v[18:19]
	s_mov_b32 m0, s80
	s_nop 0
	global_load_lds_dwordx4 v[16:17], off
	s_waitcnt vmcnt(8)
	s_waitcnt lgkmcnt(0)
	s_barrier
	s_waitcnt lgkmcnt(0)
	v_mfma_f32_16x16x32_bf16 v[16:19], v[142:145], v[194:197], v[100:103]
	v_mfma_f32_16x16x32_bf16 v[100:103], v[150:153], v[194:197], v[104:107]
	v_mfma_f32_16x16x32_bf16 v[104:107], v[142:145], v[202:205], v[108:111]
	v_mfma_f32_16x16x32_bf16 v[108:111], v[150:153], v[202:205], v[112:115]
	v_mfma_f32_16x16x32_bf16 v[112:115], v[142:145], v[210:213], v[116:119]
	v_mfma_f32_16x16x32_bf16 v[116:119], v[146:149], v[214:217], v[112:115]
	v_mfma_f32_16x16x32_bf16 v[112:115], v[150:153], v[210:213], v[120:123]
	v_mfma_f32_16x16x32_bf16 v[226:229], v[154:157], v[214:217], v[112:115]
	v_mfma_f32_16x16x32_bf16 v[112:115], v[142:145], v[218:221], v[124:127]
	v_mfma_f32_16x16x32_bf16 v[16:19], v[146:149], v[198:201], v[16:19]
	v_mfma_f32_16x16x32_bf16 v[100:103], v[154:157], v[198:201], v[100:103]
	v_mfma_f32_16x16x32_bf16 v[104:107], v[146:149], v[206:209], v[104:107]
	v_mfma_f32_16x16x32_bf16 v[108:111], v[154:157], v[206:209], v[108:111]
	v_mfma_f32_16x16x32_bf16 v[124:127], v[146:149], v[222:225], v[112:115]
	v_mfma_f32_16x16x32_bf16 v[112:115], v[150:153], v[218:221], v[130:133]
	v_mfma_f32_16x16x32_bf16 v[130:133], v[154:157], v[222:225], v[112:115]
	v_mfma_f32_16x16x32_bf16 v[80:83], v[158:161], v[210:213], v[80:83]
	v_mfma_f32_16x16x32_bf16 v[112:115], v[158:161], v[194:197], v[134:137]
	v_mfma_f32_16x16x32_bf16 v[68:71], v[186:189], v[194:197], v[68:71]
	v_mfma_f32_16x16x32_bf16 v[194:197], v[162:165], v[214:217], v[80:83]
	v_mfma_f32_16x16x32_bf16 v[80:83], v[186:189], v[210:213], v[84:87]
	v_mfma_f32_16x16x32_bf16 v[72:75], v[158:161], v[202:205], v[72:75]
	v_mfma_f32_16x16x32_bf16 v[76:79], v[186:189], v[202:205], v[76:79]
	v_mfma_f32_16x16x32_bf16 v[84:87], v[190:193], v[214:217], v[80:83]
	v_mfma_f32_16x16x32_bf16 v[80:83], v[158:161], v[218:221], v[88:91]
	v_mfma_f32_16x16x32_bf16 v[134:137], v[162:165], v[198:201], v[112:115]
	v_mfma_f32_16x16x32_bf16 v[68:71], v[190:193], v[198:201], v[68:71]
	v_mfma_f32_16x16x32_bf16 v[72:75], v[162:165], v[206:209], v[72:75]
	v_mfma_f32_16x16x32_bf16 v[76:79], v[190:193], v[206:209], v[76:79]
	v_mfma_f32_16x16x32_bf16 v[198:201], v[162:165], v[222:225], v[80:83]
	v_mfma_f32_16x16x32_bf16 v[80:83], v[186:189], v[218:221], v[92:95]
	v_mfma_f32_16x16x32_bf16 v[202:205], v[190:193], v[222:225], v[80:83]
	s_barrier
; #define PG8_STAGE(bufoff, gbase, voff) do { _Pragma("unroll") for (int _i = 0; _i < 2; ++_i) \
;         __builtin_amdgcn_global_load_lds((const unsigned*)((const char*)(gbase) + (voff)[_i]), (PG8_LAS unsigned*)(lds + (bufoff) + ldsw + _i * 8192), 16, 0, 0); } while (0)
; #define PG8_LDA(dst, b, h) do { _Pragma("unroll") for (int m = 0; m < 4; ++m) _Pragma("unroll") for (int k = 0; k < 2; ++k) dst[m][k] = *(const PG8_LAS bf16x8*)(lds + PG8_SA(b, h) + aoff + m * 2048 + k * 1024); } while (0)
; #define PG8_LDB(dst, b, h) do { _Pragma("unroll") for (int n = 0; n < 2; ++n) _Pragma("unroll") for (int k = 0; k < 2; ++k) dst[n][k] = *(const PG8_LAS bf16x8*)(lds + PG8_SB(b, h) + boff + n * 2048 + k * 1024); } while (0)
; #define PG8_MMA(ai, bj, At, Bt) do { __builtin_amdgcn_s_setprio(1); _Pragma("unroll") for (int m = 0; m < 4; ++m) _Pragma("unroll") for (int n = 0; n < 2; ++n) _Pragma("unroll") for (int k = 0; k < 2; ++k) \
;         acc[ai][bj][m][n] = __builtin_amdgcn_mfma_f32_16x16x32_bf16(Bt[n][k], At[m][k], acc[ai][bj][m][n], 0, 0, 0); __builtin_amdgcn_s_setprio(0); } while (0)
; #define PG8_WAIT_V(n) asm volatile("s_waitcnt vmcnt(" #n ")" ::: "memory")
; #define PG8_WAIT_L(n) asm volatile("s_waitcnt lgkmcnt(" #n ")" ::: "memory")
; #define PG8_BAR __builtin_amdgcn_s_barrier()
; #define PG8_SCHED __builtin_amdgcn_sched_barrier(0)
; template <class Epi, class Sched, bool ALIGN_EPI = false, bool SP2 = false>
; __device__ __forceinline__ void gemm_phase(PG8_LAS unsigned char* lds, const Gemm g, const Sched& S, const Epi& E, const int wave_id) {
;     ...
;             PG8_WAIT_V(8); PG8_WAIT_L(0); PG8_BAR; PG8_MMA(0, 0, At, B0); PG8_MMA(0, 1, At, B1); PG8_BAR; PG8_SCHED;
;             PG8_LDA(At, 0, 1); PG8_STAGE(PG8_SB(0, 0), b2, voffB); PG8_STAGE(PG8_SB(0, 1), b2 + hstep, voffB); PG8_STAGE(PG8_SA(0, 0), a2, voffA);
;             PG8_WAIT_V(8); PG8_WAIT_L(0); PG8_BAR; PG8_MMA(1, 0, At, B0); PG8_MMA(1, 1, At, B1); PG8_BAR; PG8_SCHED;
;             PG8_LDB(B0, 1, 0); PG8_LDB(B1, 1, 1); PG8_SCHED; PG8_LDA(At, 1, 0); PG8_STAGE(PG8_SA(0, 1), a2 + hstep, voffA);
;             PG8_WAIT_V(8); PG8_WAIT_L(0); PG8_BAR; PG8_MMA(0, 0, At, B0); PG8_MMA(0, 1, At, B1); PG8_BAR; PG8_SCHED;
	s_mov_b32 m0, s81
	s_nop 3
	ds_read_b128 v[80:83], v242 offset:16384
	ds_read_b128 v[88:91], v242 offset:17408
	ds_read_b128 v[92:95], v242 offset:18432
	ds_read_b128 v[112:115], v242 offset:19456
	ds_read_b128 v[120:123], v242 offset:20480
	ds_read_b128 v[206:209], v242 offset:21504
	ds_read_b128 v[210:213], v242 offset:22528
	ds_read_b128 v[214:217], v242 offset:23552
	global_load_lds_dwordx4 v[28:29], off
	s_mov_b32 m0, s82
	s_nop 0
	global_load_lds_dwordx4 v[30:31], off
	s_mov_b32 m0, s83
	s_nop 0
	global_load_lds_dwordx4 v[26:27], off
	s_mov_b32 m0, s84
	s_nop 0
	global_load_lds_dwordx4 v[20:21], off
	s_mov_b32 m0, s33
	s_nop 0
	global_load_lds_dwordx4 v[22:23], off
	s_mov_b32 m0, s63
	s_nop 0
	global_load_lds_dwordx4 v[24:25], off
	s_waitcnt vmcnt(8)
	s_waitcnt lgkmcnt(0)
	s_barrier
	s_waitcnt lgkmcnt(0)
	v_mfma_f32_16x16x32_bf16 v[20:23], v[142:145], v[80:83], v[32:35]
	v_mfma_f32_16x16x32_bf16 v[24:27], v[150:153], v[80:83], v[166:169]
	v_mfma_f32_16x16x32_bf16 v[28:31], v[142:145], v[92:95], v[170:173]
	v_mfma_f32_16x16x32_bf16 v[32:35], v[150:153], v[92:95], v[174:177]
	v_mfma_f32_16x16x32_bf16 v[40:43], v[142:145], v[210:213], v[40:43]
	v_mfma_f32_16x16x32_bf16 v[20:23], v[146:149], v[88:91], v[20:23]
	v_mfma_f32_16x16x32_bf16 v[24:27], v[154:157], v[88:91], v[24:27]
	v_mfma_f32_16x16x32_bf16 v[28:31], v[146:149], v[112:115], v[28:31]
	v_mfma_f32_16x16x32_bf16 v[32:35], v[154:157], v[112:115], v[32:35]
	v_mfma_f32_16x16x32_bf16 v[166:169], v[142:145], v[120:123], v[178:181]
	v_mfma_f32_16x16x32_bf16 v[170:173], v[150:153], v[120:123], v[182:185]
	v_mfma_f32_16x16x32_bf16 v[40:43], v[146:149], v[214:217], v[40:43]
	v_mfma_f32_16x16x32_bf16 v[48:51], v[150:153], v[210:213], v[48:51]
	v_mfma_f32_16x16x32_bf16 v[166:169], v[146:149], v[206:209], v[166:169]
	v_mfma_f32_16x16x32_bf16 v[170:173], v[154:157], v[206:209], v[170:173]
	v_mfma_f32_16x16x32_bf16 v[142:145], v[154:157], v[214:217], v[48:51]
	v_mfma_f32_16x16x32_bf16 v[48:51], v[158:161], v[80:83], v[52:55]
	v_mfma_f32_16x16x32_bf16 v[146:149], v[162:165], v[88:91], v[48:51]
	v_mfma_f32_16x16x32_bf16 v[48:51], v[186:189], v[80:83], v[56:59]
	v_mfma_f32_16x16x32_bf16 v[150:153], v[190:193], v[88:91], v[48:51]
	v_mfma_f32_16x16x32_bf16 v[48:51], v[158:161], v[92:95], v[60:63]
	v_mfma_f32_16x16x32_bf16 v[154:157], v[162:165], v[112:115], v[48:51]
	v_mfma_f32_16x16x32_bf16 v[48:51], v[186:189], v[92:95], v[64:67]
	v_mfma_f32_16x16x32_bf16 v[174:177], v[190:193], v[112:115], v[48:51]
	v_mfma_f32_16x16x32_bf16 v[48:51], v[158:161], v[120:123], v[96:99]
	v_mfma_f32_16x16x32_bf16 v[178:181], v[162:165], v[206:209], v[48:51]
	v_mfma_f32_16x16x32_bf16 v[48:51], v[186:189], v[120:123], v[138:141]
	v_mfma_f32_16x16x32_bf16 v[44:47], v[158:161], v[210:213], v[44:47]
	v_mfma_f32_16x16x32_bf16 v[36:39], v[186:189], v[210:213], v[36:39]
	v_mfma_f32_16x16x32_bf16 v[138:141], v[190:193], v[206:209], v[48:51]
	v_mfma_f32_16x16x32_bf16 v[158:161], v[162:165], v[214:217], v[44:47]
	v_mfma_f32_16x16x32_bf16 v[162:165], v[190:193], v[214:217], v[36:39]
	s_barrier
	ds_read_b128 v[64:67], v234
	ds_read_b128 v[182:185], v234 offset:1024
	ds_read_b128 v[186:189], v234 offset:2048
	ds_read_b128 v[190:193], v234 offset:3072
	ds_read_b128 v[206:209], v235
	ds_read_b128 v[210:213], v235 offset:1024
	ds_read_b128 v[214:217], v235 offset:2048
	ds_read_b128 v[218:221], v235 offset:3072
	s_mov_b32 m0, s69
	ds_read_b128 v[36:39], v242 offset:32768
	ds_read_b128 v[44:47], v242 offset:33792
	ds_read_b128 v[52:55], v242 offset:34816
	ds_read_b128 v[60:63], v242 offset:35840
	ds_read_b128 v[222:225], v242 offset:36864
	ds_read_b128 v[230:233], v242 offset:37888
	ds_read_b128 v[234:237], v242 offset:38912
	ds_read_b128 v[238:241], v242 offset:39936
	global_load_lds_dwordx4 v[12:13], off
	s_mov_b32 m0, s70
	s_nop 0
	global_load_lds_dwordx4 v[14:15], off
	s_waitcnt vmcnt(8)
	s_waitcnt lgkmcnt(0)
	s_barrier
; #define PG8_STAGE(bufoff, gbase, voff) do { _Pragma("unroll") for (int _i = 0; _i < 2; ++_i) \
;         __builtin_amdgcn_global_load_lds((const unsigned*)((const char*)(gbase) + (voff)[_i]), (PG8_LAS unsigned*)(lds + (bufoff) + ldsw + _i * 8192), 16, 0, 0); } while (0)
; #define PG8_LDA(dst, b, h) do { _Pragma("unroll") for (int m = 0; m < 4; ++m) _Pragma("unroll") for (int k = 0; k < 2; ++k) dst[m][k] = *(const PG8_LAS bf16x8*)(lds + PG8_SA(b, h) + aoff + m * 2048 + k * 1024); } while (0)
; #define PG8_MMA(ai, bj, At, Bt) do { __builtin_amdgcn_s_setprio(1); _Pragma("unroll") for (int m = 0; m < 4; ++m) _Pragma("unroll") for (int n = 0; n < 2; ++n) _Pragma("unroll") for (int k = 0; k < 2; ++k) \
;         acc[ai][bj][m][n] = __builtin_amdgcn_mfma_f32_16x16x32_bf16(Bt[n][k], At[m][k], acc[ai][bj][m][n], 0, 0, 0); __builtin_amdgcn_s_setprio(0); } while (0)
; #define PG8_WAIT_V(n) asm volatile("s_waitcnt vmcnt(" #n ")" ::: "memory")
; #define PG8_WAIT_L(n) asm volatile("s_waitcnt lgkmcnt(" #n ")" ::: "memory")
; #define PG8_BAR __builtin_amdgcn_s_barrier()
; #define PG8_SCHED __builtin_amdgcn_sched_barrier(0)
; template <class Epi, class Sched, bool ALIGN_EPI = false, bool SP2 = false>
; __device__ __forceinline__ void gemm_phase(PG8_LAS unsigned char* lds, const Gemm g, const Sched& S, const Epi& E, const int wave_id) {
;     ...
;             PG8_WAIT_V(8); PG8_WAIT_L(0); PG8_BAR; PG8_MMA(0, 0, At, B0); PG8_MMA(0, 1, At, B1); PG8_BAR; PG8_SCHED;
;             PG8_LDA(At, 1, 1); PG8_STAGE(PG8_SB(1, 0), b3, voffB); PG8_STAGE(PG8_SB(1, 1), b3 + hstep, voffB); PG8_STAGE(PG8_SA(1, 0), a3, voffA);
;             PG8_WAIT_V(8); PG8_WAIT_L(0); PG8_BAR; PG8_MMA(1, 0, At, B0); PG8_MMA(1, 1, At, B1); PG8_BAR; PG8_SCHED;
;     ...
;         }
;         if constexpr (ALIGN_EPI) { if (wr == 0) PG8_BAR; }
;         if constexpr (!Epi::AFTER_DRAIN) { E(acc, cur, wr, wc, fr, fq); S.done(cur); }
;         if (!has_next) break;
	s_waitcnt lgkmcnt(0)
	v_mfma_f32_16x16x32_bf16 v[12:15], v[64:67], v[36:39], v[16:19]
	v_mfma_f32_16x16x32_bf16 v[120:123], v[182:185], v[44:47], v[12:15]
	v_mfma_f32_16x16x32_bf16 v[12:15], v[186:189], v[36:39], v[100:103]
	v_mfma_f32_16x16x32_bf16 v[112:115], v[190:193], v[44:47], v[12:15]
	v_mfma_f32_16x16x32_bf16 v[12:15], v[64:67], v[52:55], v[104:107]
	v_mfma_f32_16x16x32_bf16 v[104:107], v[182:185], v[60:63], v[12:15]
	v_mfma_f32_16x16x32_bf16 v[12:15], v[186:189], v[52:55], v[108:111]
	v_mfma_f32_16x16x32_bf16 v[96:99], v[190:193], v[60:63], v[12:15]
	v_mfma_f32_16x16x32_bf16 v[12:15], v[64:67], v[222:225], v[116:119]
	v_mfma_f32_16x16x32_bf16 v[88:91], v[182:185], v[230:233], v[12:15]
	v_mfma_f32_16x16x32_bf16 v[12:15], v[186:189], v[222:225], v[226:229]
	v_mfma_f32_16x16x32_bf16 v[80:83], v[190:193], v[230:233], v[12:15]
	v_mfma_f32_16x16x32_bf16 v[12:15], v[64:67], v[234:237], v[124:127]
	v_mfma_f32_16x16x32_bf16 v[56:59], v[182:185], v[238:241], v[12:15]
	v_mfma_f32_16x16x32_bf16 v[12:15], v[186:189], v[234:237], v[130:133]
	v_mfma_f32_16x16x32_bf16 v[48:51], v[190:193], v[238:241], v[12:15]
	v_mfma_f32_16x16x32_bf16 v[12:15], v[206:209], v[36:39], v[134:137]
	v_mfma_f32_16x16x32_bf16 v[124:127], v[210:213], v[44:47], v[12:15]
	v_mfma_f32_16x16x32_bf16 v[12:15], v[214:217], v[36:39], v[68:71]
	v_mfma_f32_16x16x32_bf16 v[116:119], v[218:221], v[44:47], v[12:15]
	v_mfma_f32_16x16x32_bf16 v[12:15], v[206:209], v[52:55], v[72:75]
	v_mfma_f32_16x16x32_bf16 v[108:111], v[210:213], v[60:63], v[12:15]
	v_mfma_f32_16x16x32_bf16 v[12:15], v[214:217], v[52:55], v[76:79]
	v_mfma_f32_16x16x32_bf16 v[100:103], v[218:221], v[60:63], v[12:15]
	v_mfma_f32_16x16x32_bf16 v[12:15], v[206:209], v[222:225], v[194:197]
	v_mfma_f32_16x16x32_bf16 v[92:95], v[210:213], v[230:233], v[12:15]
	v_mfma_f32_16x16x32_bf16 v[12:15], v[214:217], v[222:225], v[84:87]
	v_mfma_f32_16x16x32_bf16 v[84:87], v[218:221], v[230:233], v[12:15]
	v_mfma_f32_16x16x32_bf16 v[12:15], v[206:209], v[234:237], v[198:201]
	v_mfma_f32_16x16x32_bf16 v[60:63], v[210:213], v[238:241], v[12:15]
	v_mfma_f32_16x16x32_bf16 v[12:15], v[214:217], v[234:237], v[202:205]
	v_mfma_f32_16x16x32_bf16 v[52:55], v[218:221], v[238:241], v[12:15]
	s_barrier
	s_mov_b32 m0, s87
	ds_read_b128 v[16:19], v242 offset:49152
	ds_read_b128 v[130:133], v242 offset:50176
	ds_read_b128 v[134:137], v242 offset:51200
	ds_read_b128 v[194:197], v242 offset:52224
	ds_read_b128 v[198:201], v242 offset:53248
	ds_read_b128 v[202:205], v242 offset:54272
	ds_read_b128 v[222:225], v242 offset:55296
	ds_read_b128 v[226:229], v242 offset:56320
	global_load_lds_dwordx4 v[4:5], off
	s_mov_b32 m0, s88
	s_nop 0
	global_load_lds_dwordx4 v[6:7], off
	s_mov_b32 m0, s89
	s_nop 0
	global_load_lds_dwordx4 v[8:9], off
	s_mov_b32 m0, s90
	s_nop 0
	global_load_lds_dwordx4 v[10:11], off
	s_mov_b32 m0, s73
	s_nop 0
	global_load_lds_dwordx4 v[0:1], off
	s_mov_b32 m0, s74
	s_nop 0
	global_load_lds_dwordx4 v[2:3], off
	s_waitcnt vmcnt(8)
	s_waitcnt lgkmcnt(0)
	s_barrier
	s_waitcnt lgkmcnt(0)
	v_mfma_f32_16x16x32_bf16 v[0:3], v[64:67], v[16:19], v[20:23]
	v_mfma_f32_16x16x32_bf16 v[76:79], v[182:185], v[130:133], v[0:3]
	v_mfma_f32_16x16x32_bf16 v[0:3], v[186:189], v[16:19], v[24:27]
	v_mfma_f32_16x16x32_bf16 v[68:71], v[190:193], v[130:133], v[0:3]
	v_mfma_f32_16x16x32_bf16 v[0:3], v[64:67], v[134:137], v[28:31]
	v_mfma_f32_16x16x32_bf16 v[44:47], v[182:185], v[194:197], v[0:3]
	v_mfma_f32_16x16x32_bf16 v[0:3], v[186:189], v[134:137], v[32:35]
	v_mfma_f32_16x16x32_bf16 v[36:39], v[190:193], v[194:197], v[0:3]
	v_mfma_f32_16x16x32_bf16 v[0:3], v[64:67], v[198:201], v[166:169]
	v_mfma_f32_16x16x32_bf16 v[28:31], v[182:185], v[202:205], v[0:3]
	v_mfma_f32_16x16x32_bf16 v[0:3], v[186:189], v[198:201], v[170:173]
	v_mfma_f32_16x16x32_bf16 v[20:23], v[190:193], v[202:205], v[0:3]
	v_mfma_f32_16x16x32_bf16 v[0:3], v[64:67], v[222:225], v[40:43]
	v_mfma_f32_16x16x32_bf16 v[12:15], v[182:185], v[226:229], v[0:3]
	v_mfma_f32_16x16x32_bf16 v[0:3], v[186:189], v[222:225], v[142:145]
	v_mfma_f32_16x16x32_bf16 v[4:7], v[190:193], v[226:229], v[0:3]
	v_mfma_f32_16x16x32_bf16 v[0:3], v[206:209], v[16:19], v[146:149]
	v_mfma_f32_16x16x32_bf16 v[72:75], v[210:213], v[130:133], v[0:3]
	v_mfma_f32_16x16x32_bf16 v[0:3], v[214:217], v[16:19], v[150:153]
	v_mfma_f32_16x16x32_bf16 v[64:67], v[218:221], v[130:133], v[0:3]
	v_mfma_f32_16x16x32_bf16 v[0:3], v[206:209], v[134:137], v[154:157]
	v_mfma_f32_16x16x32_bf16 v[40:43], v[210:213], v[194:197], v[0:3]
	v_mfma_f32_16x16x32_bf16 v[0:3], v[214:217], v[134:137], v[174:177]
	v_mfma_f32_16x16x32_bf16 v[32:35], v[218:221], v[194:197], v[0:3]
	v_mfma_f32_16x16x32_bf16 v[0:3], v[206:209], v[198:201], v[178:181]
	v_mfma_f32_16x16x32_bf16 v[24:27], v[210:213], v[202:205], v[0:3]
	v_mfma_f32_16x16x32_bf16 v[0:3], v[214:217], v[198:201], v[138:141]
	v_mfma_f32_16x16x32_bf16 v[16:19], v[218:221], v[202:205], v[0:3]
	v_mfma_f32_16x16x32_bf16 v[0:3], v[206:209], v[222:225], v[158:161]
	v_mfma_f32_16x16x32_bf16 v[8:11], v[210:213], v[226:229], v[0:3]
	v_mfma_f32_16x16x32_bf16 v[0:3], v[214:217], v[222:225], v[162:165]
	v_mfma_f32_16x16x32_bf16 v[0:3], v[218:221], v[226:229], v[0:3]
	s_barrier
	v_cndmask_b32_e64 v130, 0, 1, s[16:17]
	v_cmp_ne_u32_e64 s[4:5], 1, v130
	s_andn2_b64 vcc, exec, s[16:17]
	s_cbranch_vccnz .LBB0_486
	s_barrier

;     __device__ __forceinline__ bool next(int i, Unit& u) const { if (i != 0) return false; return base.next(which, u); }
;     __device__ __forceinline__ void done(const Unit& u) const {
;         if (pub == nullptr) return;
;         asm volatile("s_waitcnt vmcnt(0)" ::: "memory");
;         __builtin_amdgcn_s_barrier();
;         if (wave == 0 && lane_() == 0) { __builtin_amdgcn_fence(__ATOMIC_RELEASE, "agent"); asm volatile("s_waitcnt vmcnt(0)" ::: "memory"); __hip_atomic_fetch_add(pub + 64 * u.pm, 1u, __ATOMIC_RELAXED, __HIP_MEMORY_SCOPE_AGENT); }
;     }
; template <class Epi, class Sched, bool ALIGN_EPI = false, bool SP2 = false>
; __device__ __forceinline__ void gemm_phase(PG8_LAS unsigned char* lds, const Gemm g, const Sched& S, const Epi& E, const int wave_id) {
;     ...
;     const int wid = wave_id, tid = wave_id * 64 + lane_, lane = tid & 63, wr = wid >> 2, wc = wid & 3, fr = lane & 15, fq = lane >> 4;
;     const int K = g.K, nt = K / BK;
;     unsigned voffA[2], voffB[2];
; #pragma unroll
;     for (int i = 0; i < 2; ++i) { int R, C; stage_rc(tid * 16 + i * 8192, R, C); const int Rb = Epi::PERM ? ((R & ~31) + perm32(R & 31)) : R;
;         voffA[i] = (unsigned)(R * K + C) * 2u; voffB[i] = (unsigned)(Rb * K + C) * 2u; }
;     const size_t kstep = (size_t)(BK * 2);
;     const size_t hstep = (size_t)HALF * K * 2;
;     const size_t tstep = 2 * hstep;
;     const unsigned ldsw = (unsigned)wid * 1024u;
;     const int aoff = lds_byte(wr * 64 + fr, fq * 8), boff = lds_byte(wc * 32 + fr, fq * 8);
;     ...
;     Unit cur, nxt; int ui = 0;
;     if (!S.next(0, cur)) return;
;     f32x4 acc[2][2][4][2];
; #pragma unroll
;     for (int a = 0; a < 2; ++a)
; #pragma unroll
;         for (int b = 0; b < 2; ++b)
; #pragma unroll
;             for (int m = 0; m < 4; ++m)
; #pragma unroll
;                 for (int n = 0; n < 2; ++n) acc[a][b][m][n] = (f32x4){0.f, 0.f, 0.f, 0.f};
;     bf16x8 At[4][2], B0[2][2], B1[2][2];
;     const char* cA = (const char*)g.A + (size_t)cur.pm * tstep; const char* cB = (const char*)g.Bt + (size_t)cur.pn * tstep;
;     S.a_ready(cur);
;     if constexpr (SP2) {
;         PG8_STAGE(PG8_SB(0, 0), cB, voffB); PG8_STAGE(PG8_SB(0, 1), cB + hstep, voffB); PG8_STAGE(PG8_SA(0, 0), cA, voffA); PG8_STAGE(PG8_SA(0, 1), cA + hstep, voffA);
.LBB0_528:
	v_mbcnt_lo_u32_b32 v36, -1, 0
	v_mbcnt_hi_u32_b32 v36, -1, v36
	s_mov_b32 s0, 0x7fffe0
	s_waitcnt lgkmcnt(0)
	v_lshl_add_u32 v0, v36, 4, s56
	v_ashrrev_i32_e32 v1, 31, v0
	v_lshrrev_b32_e32 v1, 22, v1
	v_add_u32_e32 v1, v0, v1
	v_ashrrev_i32_e32 v1, 10, v1
	v_mul_i32_i24_e32 v2, 0x400, v1
	v_sub_u32_e32 v2, v0, v2
	v_lshrrev_b32_e32 v3, 4, v2
	v_bitop3_b32 v2, v3, v2, 32 bitop3:0x6c
	v_ashrrev_i32_e32 v4, 31, v2
	v_lshrrev_b32_e32 v4, 26, v4
	v_lshlrev_b32_e32 v3, 3, v1
	v_add_u32_e32 v4, v2, v4
	v_and_b32_e32 v3, -16, v3
	v_ashrrev_i32_e32 v5, 6, v4
	v_and_b32_e32 v4, 0xc0, v4
	v_add_u32_e32 v3, v5, v3
	v_sub_u32_e32 v2, v2, v4
	v_mov_b32_e32 v4, 1
	v_lshlrev_b32_e32 v1, 5, v1
	v_ashrrev_i16_sdwa v2, v4, sext(v2) dst_sel:DWORD dst_unused:UNUSED_PAD src0_sel:DWORD src1_sel:BYTE_0
	v_lshlrev_b32_e32 v6, 1, v3
	v_lshrrev_b32_e32 v7, 2, v3
	v_and_b32_e32 v5, 3, v5
	v_and_b32_e32 v1, 32, v1
	v_bfe_i32 v2, v2, 0, 16
	v_and_b32_e32 v6, 24, v6
	v_and_b32_e32 v7, 4, v7
	v_and_or_b32 v5, v3, s0, v5
	v_or3_b32 v5, v5, v7, v6
	v_add_lshl_u32 v1, v1, v2, 1
	v_add_u32_e32 v0, 0x2000, v0
	v_lshl_add_u32 v16, v3, 9, v1
	v_lshl_add_u32 v32, v5, 9, v1
	v_ashrrev_i32_e32 v1, 31, v0
	v_lshrrev_b32_e32 v1, 22, v1
	v_add_u32_e32 v1, v0, v1
	v_ashrrev_i32_e32 v1, 10, v1
	v_mul_i32_i24_e32 v2, 0x400, v1
	v_sub_u32_e32 v0, v0, v2
	v_lshrrev_b32_e32 v2, 4, v0
	v_bitop3_b32 v0, v2, v0, 32 bitop3:0x6c
	v_ashrrev_i32_e32 v3, 31, v0
	v_lshrrev_b32_e32 v3, 26, v3
	v_add_u32_e32 v3, v0, v3
	v_ashrrev_i32_e32 v5, 6, v3
	v_and_b32_e32 v3, 0xffc0, v3
	v_sub_u32_e32 v0, v0, v3
	v_lshlrev_b32_e32 v2, 3, v1
	v_lshrrev_b16_e32 v3, 7, v0
	v_and_b32_e32 v2, -16, v2
	v_and_b32_e32 v3, 1, v3
	v_add_u32_e32 v2, v5, v2
	v_add_u16_e32 v0, v0, v3
	v_and_b32_e32 v5, 3, v5
	v_lshlrev_b32_e32 v1, 5, v1
	v_ashrrev_i16_sdwa v0, v4, sext(v0) dst_sel:DWORD dst_unused:UNUSED_PAD src0_sel:DWORD src1_sel:BYTE_0
	v_lshlrev_b32_e32 v3, 1, v2
	v_lshrrev_b32_e32 v4, 2, v2
	v_and_or_b32 v5, v2, s0, v5
	v_readlane_b32 s0, v254, 19
	v_readlane_b32 s1, v254, 21
	v_and_b32_e32 v1, 32, v1
	v_bfe_i32 v0, v0, 0, 16
	v_and_b32_e32 v3, 24, v3
	v_and_b32_e32 v4, 4, v4
	s_add_i32 s0, s0, s1
	s_mov_b32 m0, s59
	v_or3_b32 v3, v5, v4, v3
	v_add_lshl_u32 v0, v1, v0, 1
	s_add_i32 s6, s0, 16
	v_lshl_add_u32 v34, v3, 9, v0
	s_ashr_i32 s7, s6, 31
	global_load_lds_dwordx4 v32, s[18:19]
	s_mov_b32 m0, s60
	s_lshl_b64 s[0:1], s[6:7], 17
	v_readlane_b32 s7, v254, 23
	global_load_lds_dwordx4 v34, s[18:19]
	s_mov_b32 m0, s61
	s_add_u32 s10, s7, s0
	v_readlane_b32 s0, v254, 11
	global_load_lds_dwordx4 v32, s[20:21]
	s_mov_b32 m0, s62
	s_addc_u32 s11, s0, s1
	global_load_lds_dwordx4 v34, s[20:21]
	s_mov_b32 m0, s33
	v_lshl_add_u32 v26, v2, 9, v0
	global_load_lds_dwordx4 v16, s[10:11]
	s_mov_b32 m0, s63
	s_add_u32 s0, s10, 0x10000
	global_load_lds_dwordx4 v26, s[10:11]
	s_addc_u32 s1, s11, 0
	s_mov_b32 m0, s69
	v_mov_b32_e32 v33, 0
	global_load_lds_dwordx4 v16, s[0:1]
	s_mov_b32 m0, s70
	v_mov_b32_e32 v35, v33
	global_load_lds_dwordx4 v26, s[0:1]
	v_mov_b32_e32 v17, v33
	v_mov_b32_e32 v27, v33
	v_lshl_add_u64 v[28:29], s[18:19], 0, v[32:33]
	v_lshl_add_u64 v[30:31], s[18:19], 0, v[34:35]
	v_lshl_add_u64 v[24:25], s[20:21], 0, v[32:33]
	v_lshl_add_u64 v[18:19], s[20:21], 0, v[34:35]
	v_lshl_add_u64 v[20:21], s[10:11], 0, v[16:17]
	v_lshl_add_u64 v[22:23], s[10:11], 0, v[26:27]
	v_lshl_add_u64 v[12:13], s[0:1], 0, v[16:17]
	v_lshl_add_u64 v[14:15], s[0:1], 0, v[26:27]
	s_waitcnt vmcnt(0)
	s_barrier
	s_waitcnt vmcnt(0)
	s_and_b64 vcc, exec, s[94:95]
	s_barrier
	s_cbranch_vccnz .LBB0_554
	v_mbcnt_lo_u32_b32 v0, -1, 0
	v_mbcnt_hi_u32_b32 v0, -1, v0
	s_nop 0
	v_cmp_eq_u32_e32 vcc, 0, v0
	s_and_saveexec_b64 s[100:101], vcc
	s_cbranch_execz .LBB0_553
	s_cmp_eq_u32 s98, 0
	s_cbranch_scc1 .Lpa3_fast
	buffer_wbl2 sc1
	s_waitcnt vmcnt(0)

; #define PG8_BAR __builtin_amdgcn_s_barrier()
; template <class Epi, class Sched, bool ALIGN_EPI = false, bool SP2 = false>
; __device__ __forceinline__ void gemm_phase(PG8_LAS unsigned char* lds, const Gemm g, const Sched& S, const Epi& E, const int wave_id) {
;     ...
;         if (wr == 1) PG8_BAR;
.LBB0_554:
	s_and_b64 vcc, exec, s[8:9]
	s_cbranch_vccnz .LBB0_556
	s_barrier
